# diff loop: loop-invariant K swizzle terms hoisted out of the tile loop
# baseline (speedup 1.0000x reference)
.LBB0_1234:
	s_waitcnt lgkmcnt(0)
	s_barrier
	v_mov_b32_e32 v14, v1
	v_mov_b32_e32 v15, v1
	v_mov_b32_e32 v0, v1
	v_mov_b32_e32 v2, v1
	v_mov_b32_e32 v3, v1
	v_mov_b32_e32 v4, v1
	v_mov_b32_e32 v5, v1
	v_mov_b32_e32 v6, v1
	v_mov_b32_e32 v7, v1
	v_mov_b32_e32 v8, v1
	v_mov_b32_e32 v9, v1
	v_mov_b32_e32 v10, v1
	v_mov_b32_e32 v11, v1
	v_mov_b32_e32 v12, v1
	v_mov_b32_e32 v13, v1
	v_mov_b64_e32 v[30:31], v[14:15]
	v_mov_b64_e32 v[46:47], v[14:15]
	v_mov_b64_e32 v[62:63], v[14:15]
	v_mov_b64_e32 v[78:79], v[14:15]
	s_xor_b64 s[38:39], s[8:9], -1
	v_lshl_add_u64 v[150:151], v[116:117], 1, s[40:41]
	s_mov_b32 s54, 0
	v_mov_b32_e32 v152, 0xf149f2ca
	v_mov_b32_e32 v129, 0
	v_mov_b64_e32 v[28:29], v[12:13]
	v_mov_b64_e32 v[26:27], v[10:11]
	v_mov_b64_e32 v[24:25], v[8:9]
	v_mov_b64_e32 v[22:23], v[6:7]
	v_mov_b64_e32 v[20:21], v[4:5]
	v_mov_b64_e32 v[18:19], v[2:3]
	v_mov_b64_e32 v[16:17], v[0:1]
	v_mov_b64_e32 v[44:45], v[12:13]
	v_mov_b64_e32 v[42:43], v[10:11]
	v_mov_b64_e32 v[40:41], v[8:9]
	v_mov_b64_e32 v[38:39], v[6:7]
	v_mov_b64_e32 v[36:37], v[4:5]
	v_mov_b64_e32 v[34:35], v[2:3]
	v_mov_b64_e32 v[32:33], v[0:1]
	v_mov_b64_e32 v[60:61], v[12:13]
	v_mov_b64_e32 v[58:59], v[10:11]
	v_mov_b64_e32 v[56:57], v[8:9]
	v_mov_b64_e32 v[54:55], v[6:7]
	v_mov_b64_e32 v[52:53], v[4:5]
	v_mov_b64_e32 v[50:51], v[2:3]
	v_mov_b64_e32 v[48:49], v[0:1]
	v_mov_b64_e32 v[76:77], v[12:13]
	v_mov_b64_e32 v[74:75], v[10:11]
	v_mov_b64_e32 v[72:73], v[8:9]
	v_mov_b64_e32 v[70:71], v[6:7]
	v_mov_b64_e32 v[68:69], v[4:5]
	v_mov_b64_e32 v[66:67], v[2:3]
	v_mov_b64_e32 v[64:65], v[0:1]
	s_mov_b32 s69, s76
	s_mov_b32 s99, s42
	s_mov_b32 s63, s5
	s_mov_b64 s[8:9], s[20:21]
	v_xor_b32_e32 v252, 32, v171
	v_xor_b32_e32 v253, 64, v171
	s_mov_b32 s78, 0
	s_mov_b32 s79, 0
	s_mov_b32 s96, 0x42200000
	s_mov_b32 s97, 0x5d800000
	s_branch .LBB0_1238

.Ldiff_redo:
	s_mul_i32 s40, s54, 0x6000
	s_add_i32 s40, s40, 0
	v_add3_u32 v0, s40, v169, v170
	v_add_u32_e32 v10, v0, v171
	v_add_u32_e32 v11, v0, v252
	v_add_u32_e32 v12, v0, v253
	v_add_u32_e32 v13, v0, v172
	ds_read_b128 v[192:195], v10
	ds_read_b128 v[196:199], v10 offset:4096
	ds_read_b128 v[200:203], v11
	ds_read_b128 v[204:207], v11 offset:4096
	ds_read_b128 v[208:211], v12
	ds_read_b128 v[212:215], v12 offset:4096
	ds_read_b128 v[216:219], v13
	ds_read_b128 v[220:223], v13 offset:4096
	s_sub_i32 s50, s72, s41
	s_cmpk_gt_i32 s50, 0x70
	s_waitcnt lgkmcnt(7)
	v_mfma_f32_32x32x16_bf16 v[96:111], v[192:195], v[224:227], 0
	s_waitcnt lgkmcnt(6)
	v_mfma_f32_32x32x16_bf16 v[80:95], v[196:199], v[224:227], 0
	s_waitcnt lgkmcnt(5)
	v_mfma_f32_32x32x16_bf16 v[96:111], v[200:203], v[228:231], v[96:111]
	s_waitcnt lgkmcnt(4)
	v_mfma_f32_32x32x16_bf16 v[80:95], v[204:207], v[228:231], v[80:95]
	s_waitcnt lgkmcnt(3)
	v_mfma_f32_32x32x16_bf16 v[96:111], v[208:211], v[232:235], v[96:111]
	s_waitcnt lgkmcnt(2)
	v_mfma_f32_32x32x16_bf16 v[80:95], v[212:215], v[232:235], v[80:95]
	s_waitcnt lgkmcnt(1)
	v_mfma_f32_32x32x16_bf16 v[96:111], v[216:219], v[236:239], v[96:111]
	s_waitcnt lgkmcnt(0)
	v_mfma_f32_32x32x16_bf16 v[80:95], v[220:223], v[236:239], v[80:95]
	s_cbranch_scc1 .LBB0_1241
	v_or_b32_e32 v0, s41, v122
	v_sub_u32_e32 v0, v128, v0
	v_add_u32_e32 v153, -1, v0
	v_subrev_u32_e32 v178, 33, v0
	v_subrev_u32_e32 v179, 32, v0
	v_subrev_u32_e32 v198, 34, v0
	v_med3_i32 v2, v0, 0, v181
	v_med3_i32 v3, v153, 0, v181
	v_med3_i32 v4, v179, 0, v181
	v_med3_i32 v5, v178, 0, v181
	v_add_u32_e32 v191, -3, v0
	v_add_u32_e32 v196, -2, v0
	v_subrev_u32_e32 v197, 35, v0
	v_med3_i32 v8, v198, 0, v181
	v_lshl_add_u32 v2, v2, 2, s82
	v_lshl_add_u32 v3, v3, 2, s82
	v_lshl_add_u32 v4, v4, 2, s82
	v_lshl_add_u32 v5, v5, 2, s82
	v_med3_i32 v6, v196, 0, v181
	v_med3_i32 v7, v191, 0, v181
	v_lshl_add_u32 v12, v8, 2, s82
	v_med3_i32 v8, v197, 0, v181
	v_lshl_add_u32 v6, v6, 2, s82
	v_lshl_add_u32 v7, v7, 2, s82
	v_lshl_add_u32 v13, v8, 2, s82
	ds_read_b32 v8, v2
	ds_read_b32 v9, v3
	ds_read_b32 v4, v4
	ds_read_b32 v5, v5
	ds_read_b32 v10, v6
	ds_read_b32 v11, v7
	ds_read_b32 v2, v12
	ds_read_b32 v3, v13
	v_subrev_u32_e32 v202, 40, v0
	v_subrev_u32_e32 v201, 41, v0
	v_med3_i32 v12, v202, 0, v181
	v_lshl_add_u32 v14, v12, 2, s82
	v_med3_i32 v12, v201, 0, v181
	v_add_u32_e32 v204, -10, v0
	v_lshl_add_u32 v15, v12, 2, s82
	v_add_u32_e32 v203, -11, v0
	v_med3_i32 v12, v204, 0, v181
	v_add_u32_e32 v199, -9, v0
	v_add_u32_e32 v200, -8, v0
	v_lshl_add_u32 v154, v12, 2, s82
	v_med3_i32 v12, v203, 0, v181
	v_subrev_u32_e32 v206, 42, v0
	v_med3_i32 v6, v200, 0, v181
	v_med3_i32 v7, v199, 0, v181
	v_lshl_add_u32 v155, v12, 2, s82
	v_subrev_u32_e32 v205, 43, v0
	v_med3_i32 v12, v206, 0, v181
	v_lshl_add_u32 v6, v6, 2, s82
	v_lshl_add_u32 v7, v7, 2, s82
	v_lshl_add_u32 v156, v12, 2, s82
	v_med3_i32 v12, v205, 0, v181
	v_lshl_add_u32 v157, v12, 2, s82
	ds_read_b32 v12, v6
	ds_read_b32 v13, v7
	ds_read_b32 v14, v14
	ds_read_b32 v15, v15
	ds_read_b32 v154, v154
	ds_read_b32 v155, v155
	ds_read_b32 v6, v156
	ds_read_b32 v7, v157
	v_subrev_u32_e32 v207, 17, v0
	v_add_u32_e32 v208, -16, v0
	v_subrev_u32_e32 v209, 49, v0
	v_subrev_u32_e32 v210, 48, v0
	v_subrev_u32_e32 v211, 19, v0
	v_subrev_u32_e32 v212, 18, v0
	v_subrev_u32_e32 v213, 51, v0
	v_subrev_u32_e32 v214, 50, v0
	v_med3_i32 v156, v208, 0, v181
	v_med3_i32 v157, v207, 0, v181
	v_med3_i32 v158, v210, 0, v181
	v_med3_i32 v159, v209, 0, v181
	v_med3_i32 v160, v212, 0, v181
	v_med3_i32 v161, v211, 0, v181
	v_med3_i32 v162, v214, 0, v181
	v_med3_i32 v163, v213, 0, v181
	v_lshl_add_u32 v156, v156, 2, s82
	v_lshl_add_u32 v157, v157, 2, s82
	v_lshl_add_u32 v158, v158, 2, s82
	v_lshl_add_u32 v159, v159, 2, s82
	v_lshl_add_u32 v160, v160, 2, s82
	v_lshl_add_u32 v161, v161, 2, s82
	v_lshl_add_u32 v162, v162, 2, s82
	v_lshl_add_u32 v163, v163, 2, s82
	ds_read_b32 v156, v156
	ds_read_b32 v157, v157
	ds_read_b32 v158, v158
	ds_read_b32 v159, v159
	ds_read_b32 v160, v160
	ds_read_b32 v161, v161
	ds_read_b32 v162, v162
	ds_read_b32 v163, v163
	s_waitcnt lgkmcnt(14)
	v_pk_add_f32 v[10:11], v[98:99], v[10:11]
	v_cmp_gt_u32_e32 vcc, 2.0, v191
	v_pk_add_f32 v[8:9], v[96:97], v[8:9]
	v_pk_add_f32 v[12:13], v[100:101], v[12:13]
	v_cndmask_b32_e32 v99, v182, v11, vcc
	v_cmp_gt_u32_e32 vcc, 2.0, v196
	s_waitcnt lgkmcnt(10)
	v_pk_add_f32 v[100:101], v[102:103], v[154:155]
	v_subrev_u32_e32 v215, 25, v0
	v_cndmask_b32_e32 v98, v182, v10, vcc
	v_cmp_gt_u32_e32 vcc, 2.0, v153
	v_subrev_u32_e32 v216, 24, v0
	v_subrev_u32_e32 v217, 57, v0
	v_cndmask_b32_e32 v97, v182, v9, vcc
	v_cmp_gt_u32_e32 vcc, 2.0, v0
	v_subrev_u32_e32 v218, 56, v0
	v_subrev_u32_e32 v219, 27, v0
	v_cndmask_b32_e32 v96, v182, v8, vcc
	v_cmp_gt_u32_e32 vcc, 2.0, v203
	v_subrev_u32_e32 v220, 26, v0
	v_subrev_u32_e32 v221, 59, v0
	v_cndmask_b32_e32 v103, v182, v101, vcc
	v_cmp_gt_u32_e32 vcc, 2.0, v204
	v_subrev_u32_e32 v222, 58, v0
	v_med3_i32 v164, v216, 0, v181
	v_cndmask_b32_e32 v102, v182, v100, vcc
	v_cmp_gt_u32_e32 vcc, 2.0, v199
	v_med3_i32 v165, v215, 0, v181
	v_med3_i32 v166, v218, 0, v181
	v_cndmask_b32_e32 v101, v182, v13, vcc
	v_cmp_gt_u32_e32 vcc, 2.0, v200
	v_med3_i32 v167, v217, 0, v181
	v_med3_i32 v192, v220, 0, v181
	v_med3_i32 v193, v219, 0, v181
	v_med3_i32 v194, v222, 0, v181
	v_med3_i32 v195, v221, 0, v181
	s_waitcnt lgkmcnt(2)
	v_pk_add_f32 v[106:107], v[106:107], v[160:161]
	v_cndmask_b32_e32 v100, v182, v12, vcc
	v_cmp_gt_u32_e32 vcc, 2.0, v211
	v_lshl_add_u32 v164, v164, 2, s82
	v_lshl_add_u32 v165, v165, 2, s82
	v_lshl_add_u32 v166, v166, 2, s82
	v_lshl_add_u32 v167, v167, 2, s82
	v_lshl_add_u32 v192, v192, 2, s82
	v_lshl_add_u32 v193, v193, 2, s82
	v_lshl_add_u32 v194, v194, 2, s82
	v_lshl_add_u32 v195, v195, 2, s82
	v_cndmask_b32_e32 v107, v182, v107, vcc
	v_cmp_gt_u32_e32 vcc, 2.0, v212
	ds_read_b32 v164, v164
	ds_read_b32 v165, v165
	ds_read_b32 v166, v166
	ds_read_b32 v192, v192
	ds_read_b32 v193, v193
	ds_read_b32 v194, v194
	ds_read_b32 v195, v195
	ds_read_b32 v167, v167
	v_pk_add_f32 v[104:105], v[104:105], v[156:157]
	v_cndmask_b32_e32 v106, v182, v106, vcc
	v_cmp_gt_u32_e32 vcc, 2.0, v207
	s_waitcnt lgkmcnt(3)
	v_pk_add_f32 v[110:111], v[110:111], v[192:193]
	v_pk_add_f32 v[108:109], v[108:109], v[164:165]
	v_cndmask_b32_e32 v105, v182, v105, vcc
	v_cmp_gt_u32_e32 vcc, 2.0, v208
	v_pk_add_f32 v[2:3], v[82:83], v[2:3]
	v_pk_add_f32 v[4:5], v[80:81], v[4:5]
	v_cndmask_b32_e32 v104, v182, v104, vcc
	v_cmp_gt_u32_e32 vcc, 2.0, v219
	v_pk_add_f32 v[6:7], v[86:87], v[6:7]
	v_pk_add_f32 v[14:15], v[84:85], v[14:15]
	v_cndmask_b32_e32 v111, v182, v111, vcc
	v_cmp_gt_u32_e32 vcc, 2.0, v220
	v_pk_add_f32 v[12:13], v[88:89], v[158:159]
	v_pk_add_f32 v[88:89], v[90:91], v[162:163]
	v_cndmask_b32_e32 v110, v182, v110, vcc
	v_cmp_gt_u32_e32 vcc, 2.0, v215
	s_waitcnt lgkmcnt(1)
	v_pk_add_f32 v[10:11], v[94:95], v[194:195]
	s_waitcnt lgkmcnt(0)
	v_pk_add_f32 v[8:9], v[92:93], v[166:167]
	v_cndmask_b32_e32 v109, v182, v109, vcc
	v_cmp_gt_u32_e32 vcc, 2.0, v216
	s_nop 1
	v_cndmask_b32_e32 v108, v182, v108, vcc
	v_cmp_gt_u32_e32 vcc, 2.0, v197
	s_nop 1
	v_cndmask_b32_e32 v83, v182, v3, vcc
	v_cmp_gt_u32_e32 vcc, 2.0, v198
	s_nop 1
	v_cndmask_b32_e32 v82, v182, v2, vcc
	v_cmp_gt_u32_e32 vcc, 2.0, v178
	s_nop 1
	v_cndmask_b32_e32 v81, v182, v5, vcc
	v_cmp_gt_u32_e32 vcc, 2.0, v179
	s_nop 1
	v_cndmask_b32_e32 v80, v182, v4, vcc
	v_cmp_gt_u32_e32 vcc, 2.0, v205
	s_nop 1
	v_cndmask_b32_e32 v87, v182, v7, vcc
	v_cmp_gt_u32_e32 vcc, 2.0, v206
	s_nop 1
	v_cndmask_b32_e32 v86, v182, v6, vcc
	v_cmp_gt_u32_e32 vcc, 2.0, v201
	s_nop 1
	v_cndmask_b32_e32 v85, v182, v15, vcc
	v_cmp_gt_u32_e32 vcc, 2.0, v202
	s_nop 1
	v_cndmask_b32_e32 v84, v182, v14, vcc
	v_cmp_gt_u32_e32 vcc, 2.0, v213
	s_nop 1
	v_cndmask_b32_e32 v91, v182, v89, vcc
	v_cmp_gt_u32_e32 vcc, 2.0, v214
	s_nop 1
	v_cndmask_b32_e32 v90, v182, v88, vcc
	v_cmp_gt_u32_e32 vcc, 2.0, v209
	s_nop 1
	v_cndmask_b32_e32 v89, v182, v13, vcc
	v_cmp_gt_u32_e32 vcc, 2.0, v210
	s_nop 1
	v_cndmask_b32_e32 v88, v182, v12, vcc
	v_cmp_gt_u32_e32 vcc, 2.0, v221
	s_nop 1
	v_cndmask_b32_e32 v95, v182, v11, vcc
	v_cmp_gt_u32_e32 vcc, 2.0, v222
	s_nop 1
	v_cndmask_b32_e32 v94, v182, v10, vcc
	v_cmp_gt_u32_e32 vcc, 2.0, v217
	s_nop 1
	v_cndmask_b32_e32 v93, v182, v9, vcc
	v_cmp_gt_u32_e32 vcc, 2.0, v218
	s_nop 1
	v_cndmask_b32_e32 v92, v182, v8, vcc
